# transposes spread over idle workgroups of both the in-projection GEMM (w_out,w_up,next w_in) and the up GEMM (w_down); trampolined direct branches into the phase-0 loop
# speedup vs baseline: 1.0695x; 1.0075x over previous
.LBB0_271:
	s_cmp_lt_u32 s62, 0x94
	s_cbranch_scc1 .Ltr_skip
	v_writelane_b32 v130, s8, 0
	v_writelane_b32 v130, s9, 1
	v_writelane_b32 v130, s10, 2
	v_writelane_b32 v130, s11, 3
	v_writelane_b32 v130, s12, 4
	v_writelane_b32 v130, s13, 5
	v_writelane_b32 v130, s14, 6
	v_writelane_b32 v130, s15, 7
	v_writelane_b32 v130, s16, 8
	v_writelane_b32 v130, s17, 9
	v_writelane_b32 v130, s20, 10
	v_writelane_b32 v130, s22, 11
	v_writelane_b32 v130, s33, 12
	v_writelane_b32 v130, s70, 13
	v_mov_b32_e32 v131, v79
	v_mov_b32_e32 v132, v103
	v_readlane_b32 s0, v254, 47
	s_waitcnt vmcnt(0) lgkmcnt(0)
	s_barrier
	s_mov_b64 s[8:9], s[60:61]
	s_load_dwordx2 s[4:5], s[8:9], 0xc0
	s_lshr_b32 s16, s68, 6
	v_mbcnt_lo_u32_b32 v25, -1, 0
	v_mbcnt_hi_u32_b32 v25, -1, v25
	v_and_b32_e32 v24, 63, v25
	s_sub_i32 s1, s62, 0x94
	s_lshl_b32 s1, s1, 3
	s_add_i32 s1, s1, s16
	s_movk_i32 s22, 0x1880
	s_movk_i32 s101, 0x257f
	s_mov_b32 s100, 1
	s_cmp_eq_u32 s0, 0
	s_cbranch_scc0 .Ltr_l1
	s_movk_i32 s22, 0x300
	s_movk_i32 s101, 0xfff
	s_mov_b32 s100, 2
.Ltr_l1:
	s_add_i32 s22, s22, s1
	s_movk_i32 s70, 0x360
	s_waitcnt lgkmcnt(0)
	s_cmp_gt_i32 s22, s101
	s_cbranch_scc1 .Ltr_ret
	s_branch .Ltr_entry

.Ltr_ret:
	s_cmp_eq_u32 s100, 3
	s_cbranch_scc1 .Ltr_t1r
	s_cmp_eq_u32 s100, 2
	s_cbranch_scc0 .Ltr_fin
	s_mov_b32 s100, 1
	s_mov_b64 s[8:9], s[60:61]
	s_load_dwordx2 s[4:5], s[8:9], 0xc0
	s_lshr_b32 s16, s68, 6
	v_mbcnt_lo_u32_b32 v25, -1, 0
	v_mbcnt_hi_u32_b32 v25, -1, v25
	v_and_b32_e32 v24, 63, v25
	s_sub_i32 s1, s62, 0x94
	s_lshl_b32 s1, s1, 3
	s_add_i32 s1, s1, s16
	s_add_i32 s22, s1, 0x1580
	s_movk_i32 s101, 0x187f
	s_movk_i32 s70, 0x360
	s_waitcnt lgkmcnt(0)
	s_cmp_gt_i32 s22, s101
	s_cbranch_scc1 .Ltr_fin
	s_branch .Ltr_entry
.Ltr_fin:
	s_nop 0
	v_readlane_b32 s8, v130, 0
	v_readlane_b32 s9, v130, 1
	v_readlane_b32 s10, v130, 2
	v_readlane_b32 s11, v130, 3
	v_readlane_b32 s12, v130, 4
	v_readlane_b32 s13, v130, 5
	v_readlane_b32 s14, v130, 6
	v_readlane_b32 s15, v130, 7
	v_readlane_b32 s16, v130, 8
	v_readlane_b32 s17, v130, 9
	v_readlane_b32 s20, v130, 10
	v_readlane_b32 s22, v130, 11
	v_readlane_b32 s33, v130, 12
	v_readlane_b32 s70, v130, 13
	v_mov_b32_e32 v79, v131
	v_mov_b32_e32 v103, v132
	s_mov_b32 s100, 0
	s_nop 4

.LBB0_520:
	s_lshl_b32 s20, s36, 6
	s_add_i32 s82, s20, 0x500
	s_lshl_b64 s[0:1], s[82:83], 2
	s_add_u32 s0, s34, s0
	s_addc_u32 s1, s35, s1
	v_mov_b64_e32 v[4:5], s[0:1]
	flat_atomic_add v3, v[4:5], v209 sc0
	v_cvt_f32_u32_e32 v1, v2
	v_sub_u32_e32 v4, 0, v2
	v_rcp_iflag_f32_e32 v1, v1
	s_nop 0
	v_mul_f32_e32 v1, 0x4f7ffffe, v1
	v_cvt_u32_f32_e32 v1, v1
	v_mul_lo_u32 v4, v4, v1
	v_mul_hi_u32 v4, v1, v4
	v_add_u32_e32 v1, v1, v4
	s_waitcnt vmcnt(0) lgkmcnt(0)
	v_mul_hi_u32 v1, v3, v1
	v_mul_lo_u32 v4, v1, v2
	v_sub_u32_e32 v4, v3, v4
	v_cmp_ge_u32_e32 vcc, v4, v2
	v_add_u32_e32 v5, 1, v1
	s_nop 0
	v_cndmask_b32_e32 v1, v1, v5, vcc
	v_sub_u32_e32 v5, v4, v2
	v_cndmask_b32_e32 v4, v4, v5, vcc
	v_cmp_ge_u32_e32 vcc, v4, v2
	v_add_u32_e32 v4, 1, v1
	s_nop 0
	v_cndmask_b32_e32 v1, v1, v4, vcc
	v_add_u32_e32 v4, 1, v3
	v_mad_u64_u32 v[2:3], s[0:1], v2, v1, v[2:3]
	v_cmp_ne_u32_e32 vcc, v4, v2
	s_and_saveexec_b64 s[0:1], vcc
	s_xor_b64 s[0:1], exec, s[0:1]
	s_cbranch_execz .LBB0_533
	s_movk_i32 s82, 0xd40
	s_lshl_b64 s[2:3], s[82:83], 2
	s_add_u32 s4, s34, s2
	s_addc_u32 s5, s35, s3
	v_mov_b64_e32 v[2:3], s[4:5]
	flat_load_dword v0, v[2:3] sc1
	s_waitcnt vmcnt(0) lgkmcnt(0)
	v_cmp_eq_u32_e32 vcc, v0, v1
	s_and_saveexec_b64 s[2:3], vcc
	s_cbranch_execz .LBB0_532
	s_mov_b32 s21, 1
	s_mov_b64 s[6:7], 0
	s_branch .LBB0_524
.Ltr_t1e:
	s_branch .Ltr_t2e
.Ltr_t1r:
	s_branch .Ltr8_ret
.LBB0_523:
	s_or_b64 exec, exec, s[16:17]
	s_and_b64 s[12:13], exec, s[12:13]
	s_or_b64 s[6:7], s[12:13], s[6:7]
	s_andn2_b64 s[8:9], s[8:9], exec
	s_and_b64 s[12:13], s[10:11], exec
	s_or_b64 s[8:9], s[8:9], s[12:13]
	s_andn2_b64 exec, exec, s[6:7]
	s_cbranch_execz .LBB0_530

.LBB0_871:
	v_readlane_b32 s0, v254, 47
	s_movk_i32 s1, 0xd8
	s_nop 2
	s_cmp_eq_u32 s0, 0
	s_cbranch_scc1 .Ltr8_a
	s_movk_i32 s1, 0x80
.Ltr8_a:
	s_cmp_lt_u32 s62, s1
	s_cbranch_scc1 .Ltr8_skip
	v_writelane_b32 v130, s8, 0
	v_writelane_b32 v130, s9, 1
	v_writelane_b32 v130, s10, 2
	v_writelane_b32 v130, s11, 3
	v_writelane_b32 v130, s12, 4
	v_writelane_b32 v130, s13, 5
	v_writelane_b32 v130, s14, 6
	v_writelane_b32 v130, s15, 7
	v_writelane_b32 v130, s16, 8
	v_writelane_b32 v130, s17, 9
	v_writelane_b32 v130, s20, 10
	v_writelane_b32 v130, s22, 11
	v_writelane_b32 v130, s33, 12
	v_writelane_b32 v130, s70, 13
	v_mov_b32_e32 v131, v79
	v_mov_b32_e32 v132, v103
	s_waitcnt vmcnt(0) lgkmcnt(0)
	s_barrier
	s_mov_b64 s[8:9], s[60:61]
	s_load_dwordx2 s[4:5], s[8:9], 0xc0
	s_lshr_b32 s16, s68, 6
	v_mbcnt_lo_u32_b32 v25, -1, 0
	v_mbcnt_hi_u32_b32 v25, -1, v25
	v_and_b32_e32 v24, 63, v25
	s_sub_i32 s1, s62, s1
	s_lshl_b32 s1, s1, 3
	s_add_i32 s1, s1, s16
	s_add_i32 s22, s1, 0x2580
	s_movk_i32 s101, 0x2aff
	s_movk_i32 s70, 0x400
	s_cmp_eq_u32 s0, 0
	s_cbranch_scc0 .Ltr8_l1
	s_add_i32 s22, s1, 0x1000
	s_movk_i32 s101, 0x157f
	s_movk_i32 s70, 0x140
.Ltr8_l1:
	s_mov_b32 s100, 3
	s_waitcnt lgkmcnt(0)
	s_cmp_gt_i32 s22, s101
	s_cbranch_scc1 .Ltr8_ret
	s_branch .Ltr_t1e
